# v11 + GEMM phase prologue: removed redundant vmcnt(0) between the two first-stage load groups
# baseline (speedup 1.0000x reference)
; #define PG8_STAGE(bufoff, gbase, voff) do { _Pragma("unroll") for (int _i = 0; _i < 2; ++_i) \
;         __builtin_amdgcn_global_load_lds((const unsigned*)((const char*)(gbase) + (voff)[_i]), (PG8_LAS unsigned*)(lds + (bufoff) + ldsw + _i * 8192), 16, 0, 0); } while (0)
; template <class Epi, class Sched, bool ALIGN_EPI = false, bool SP2 = false>
; __device__ __forceinline__ void gemm_phase(PG8_LAS unsigned char* lds, const Gemm g, const Sched& S, const Epi& E) {
;     ...
;     const int tid = tid_, wid = __builtin_amdgcn_readfirstlane(tid >> 6), lane = tid & 63, wr = wid >> 2, wc = wid & 3, fr = lane & 15, fq = lane >> 4;
;     const int K = g.K, nt = K / BK;
;     unsigned voffA[2], voffB[2];
; #pragma unroll
;     for (int i = 0; i < 2; ++i) { int R, C; stage_rc(tid * 16 + i * 8192, R, C); const int Rb = Epi::PERM ? ((R & ~31) + perm32(R & 31)) : R;
;         voffA[i] = (unsigned)(R * K + C) * 2u; voffB[i] = (unsigned)(Rb * K + C) * 2u; }
;     const size_t kstep = (size_t)(BK * 2);
;     const size_t hstep = (size_t)HALF * K * 2;
;     const size_t tstep = 2 * hstep;
;     const unsigned ldsw = (unsigned)wid * 1024u;
;     const int aoff = lds_byte(wr * 64 + fr, fq * 8), boff = lds_byte(wc * 32 + fr, fq * 8);
;     ...
;     const char* cA = (const char*)g.A + (size_t)cur.pm * tstep; const char* cB = (const char*)g.Bt + (size_t)cur.pn * tstep;
;     S.a_ready(cur);
;     if constexpr (SP2) {
;         PG8_STAGE(PG8_SB(0, 0), cB, voffB); PG8_STAGE(PG8_SB(0, 1), cB + hstep, voffB); PG8_STAGE(PG8_SA(0, 0), cA, voffA); PG8_STAGE(PG8_SA(0, 1), cA + hstep, voffA);
.LBB0_214:
	s_andn2_b64 vcc, exec, s[12:13]
	s_cbranch_vccnz .LBB0_258
	v_bfe_i32 v3, v15, 27, 1
	v_lshlrev_b32_e32 v2, 4, v15
	v_lshrrev_b32_e32 v3, 22, v3
	v_add_u32_e32 v3, v2, v3
	v_and_b32_e32 v3, 0xfffffc00, v3
	v_sub_u32_e32 v3, v2, v3
	v_ashrrev_i32_e32 v0, 31, v15
	v_lshrrev_b32_e32 v4, 4, v3
	v_lshrrev_b32_e32 v0, 26, v0
	v_bitop3_b32 v3, v4, v3, 32 bitop3:0x6c
	v_add_u32_e32 v0, v15, v0
	v_ashrrev_i32_e32 v5, 31, v3
	v_ashrrev_i32_e32 v0, 6, v0
	v_lshrrev_b32_e32 v5, 26, v5
	v_lshlrev_b32_e32 v4, 3, v0
	v_add_u32_e32 v5, v3, v5
	v_and_b32_e32 v4, -16, v4
	v_ashrrev_i32_e32 v6, 6, v5
	v_lshlrev_b32_e32 v0, 5, v0
	v_add_u32_e32 v4, v6, v4
	v_and_b32_e32 v16, 32, v0
	v_and_b32_e32 v0, 0xc0, v5
	v_sub_u32_e32 v0, v3, v0
	v_lshlrev_b32_e32 v3, 1, v4
	v_lshrrev_b32_e32 v5, 2, v4
	v_and_b32_e32 v6, 3, v6
	s_mov_b32 s9, 0x7fffffe0
	v_ashrrev_i16_sdwa v0, v194, sext(v0) dst_sel:DWORD dst_unused:UNUSED_PAD src0_sel:DWORD src1_sel:BYTE_0
	v_and_b32_e32 v3, 24, v3
	v_and_b32_e32 v5, 4, v5
	v_and_or_b32 v6, v4, s9, v6
	v_bfe_i32 v17, v0, 0, 16
	v_or3_b32 v3, v6, v5, v3
	v_add_u32_e32 v0, v16, v17
	v_mul_lo_u32 v18, v4, s6
	v_mul_lo_u32 v3, v3, s6
	v_add_u32_e32 v2, 0x2000, v2
	s_waitcnt vmcnt(0)
	v_add_lshl_u32 v158, v0, v18, 1
	v_add_lshl_u32 v0, v3, v0, 1
	v_ashrrev_i32_e32 v3, 31, v2
	v_lshrrev_b32_e32 v3, 22, v3
	v_add_u32_e32 v3, v2, v3
	v_ashrrev_i32_e32 v3, 10, v3
	v_mul_i32_i24_e32 v4, 0x400, v3
	v_sub_u32_e32 v2, v2, v4
	s_lshl_b32 s50, s6, 8
	s_mov_b32 s51, s95
	v_lshrrev_b32_e32 v4, 4, v2
	s_lshl_b64 s[52:53], s[50:51], 1
	s_ashr_i32 s10, s26, 31
	v_bitop3_b32 v2, v4, v2, 32 bitop3:0x6c
	s_mul_i32 s10, s52, s10
	s_mul_hi_u32 s11, s52, s26
	v_ashrrev_i32_e32 v5, 31, v2
	s_add_i32 s10, s11, s10
	s_bfe_u32 s11, s6, 0x10017
	v_lshrrev_b32_e32 v5, 26, v5
	s_mul_i32 s12, s11, s26
	v_lshlrev_b32_e32 v4, 3, v3
	v_add_u32_e32 v5, v2, v5
	s_add_i32 s14, s10, s12
	s_ashr_i32 s10, s27, 31
	v_and_b32_e32 v4, -16, v4
	v_ashrrev_i32_e32 v6, 6, v5
	s_mul_i32 s10, s52, s10
	s_mul_hi_u32 s12, s52, s27
	s_ashr_i32 s8, s7, 6
	v_add_u32_e32 v4, v6, v4
	v_lshlrev_b32_e32 v3, 5, v3
	v_and_b32_e32 v6, 3, v6
	s_add_i32 s10, s12, s10
	s_mul_i32 s11, s11, s27
	v_and_b32_e32 v19, 32, v3
	v_and_b32_e32 v3, 0xc0, v5
	v_and_or_b32 v6, v4, s9, v6
	s_ashr_i32 s9, s7, 8
	s_lshl_b32 s21, s8, 10
	s_add_i32 s10, s10, s11
	s_mul_i32 s11, s52, s27
	v_sub_u32_e32 v2, v2, v3
	v_lshlrev_b32_e32 v3, 1, v4
	v_lshrrev_b32_e32 v5, 2, v4
	s_add_u32 s12, s44, s11
	v_ashrrev_i16_sdwa v2, v194, sext(v2) dst_sel:DWORD dst_unused:UNUSED_PAD src0_sel:DWORD src1_sel:BYTE_0
	v_and_b32_e32 v3, 24, v3
	v_and_b32_e32 v5, 4, v5
	s_addc_u32 s13, s45, s10
	s_add_i32 s36, s21, 0
	v_bfe_i32 v20, v2, 0, 16
	v_or3_b32 v3, v6, v5, v3
	s_add_i32 m0, s36, 0x10000
	v_add_u32_e32 v2, v19, v20
	v_mul_lo_u32 v3, v3, s6
	global_load_lds_dwordx4 v0, s[12:13]
	s_add_i32 m0, s36, 0x12000
	v_add_lshl_u32 v164, v3, v2, 1
	s_add_u32 s10, s12, s50
	global_load_lds_dwordx4 v164, s[12:13]
	s_addc_u32 s11, s13, 0
	s_add_i32 m0, s36, 0x14000
	s_mul_i32 s16, s52, s26
	global_load_lds_dwordx4 v0, s[10:11]
	s_add_i32 m0, s36, 0x16000
	s_add_u32 s16, s46, s16
	s_addc_u32 s17, s47, s14
	s_add_i32 s37, s36, 0x2000
	v_mul_lo_u32 v21, v4, s6
	global_load_lds_dwordx4 v164, s[10:11]
	s_mov_b32 m0, s36
	s_add_u32 s38, s16, s50
	v_add_lshl_u32 v160, v2, v21, 1
	global_load_lds_dwordx4 v158, s[16:17]
	s_mov_b32 m0, s37
	s_addc_u32 s39, s17, 0
	s_add_i32 s64, s36, 0x4000
	global_load_lds_dwordx4 v160, s[16:17]
	s_mov_b32 m0, s64
	s_add_i32 s65, s36, 0x6000
	global_load_lds_dwordx4 v158, s[38:39]
	s_mov_b32 m0, s65
	v_mov_b32_e32 v165, v1
	global_load_lds_dwordx4 v160, s[38:39]
	v_mov_b32_e32 v159, v1
	v_mov_b32_e32 v161, v1
	s_cmp_eq_u32 s9, 1
	s_mov_b64 s[18:19], s[62:63]
	v_lshl_add_u64 v[10:11], s[12:13], 0, v[0:1]
	v_lshl_add_u64 v[6:7], s[12:13], 0, v[164:165]
	v_lshl_add_u64 v[4:5], s[10:11], 0, v[0:1]
	v_lshl_add_u64 v[2:3], s[10:11], 0, v[164:165]
	v_lshl_add_u64 v[8:9], s[16:17], 0, v[158:159]
	s_cselect_b64 s[54:55], -1, 0
	s_cmp_lg_u32 s9, 1
	v_lshl_add_u64 v[12:13], s[16:17], 0, v[160:161]
	s_cbranch_scc1 .LBB0_217
	s_barrier
